# post-loop counted vmcnt per epilogue kind; ctx GEMM entry syncs no longer drain stores
# baseline (speedup 1.0000x reference)
; #define PG8_WAIT_V(n) asm volatile("s_waitcnt vmcnt(" #n ")" ::: "memory")
; #define PG8_BAR __builtin_amdgcn_s_barrier()
; template <class Epi, class Sched, bool ALIGN_EPI = false, bool SP2 = false>
; __device__ __forceinline__ void gemm_phase(PG8_LAS unsigned char* lds, const Gemm g, const Sched& S, const Epi& E) {
;     ...
;     PG8_WAIT_V(0);
;     if constexpr (!ALIGN_EPI) { if (wr == 0) PG8_BAR; }
;     PG8_BAR;
.LBB0_563:
	s_cmp_eq_u32 s0, 0
	s_cbranch_scc1 .Lpl_k0
	s_cmp_eq_u32 s0, 2
	s_cbranch_scc1 .Lpl_k2
	s_waitcnt vmcnt(63)
	s_branch .Lpl_done
.Lpl_k0:
	s_waitcnt vmcnt(8)
	s_branch .Lpl_done
.Lpl_k2:
	s_waitcnt vmcnt(16)
.Lpl_done:
	v_readlane_b32 s80, v247, 0
	v_readlane_b32 s92, v247, 2
	v_readlane_b32 s94, v247, 4
	v_readlane_b32 s96, v246, 8
	v_readlane_b32 s98, v246, 10
	v_readlane_b32 s16, v246, 0
	v_readlane_b32 s44, v246, 2
	v_readlane_b32 s54, v246, 4
	v_readlane_b32 s36, v246, 6
	v_readlane_b32 s81, v247, 1
	v_readlane_b32 s93, v247, 3
	v_readlane_b32 s95, v247, 5
	v_readlane_b32 s97, v246, 9
	v_readlane_b32 s99, v246, 11
	v_readlane_b32 s17, v246, 1
	v_readlane_b32 s45, v246, 3
	v_readlane_b32 s55, v246, 5
	v_readlane_b32 s37, v246, 7
	s_barrier

; __global__ void __launch_bounds__(512, 2) fwd_megakernel(Args a_) {
;     ...
;                 } else if ((k == 1 || k == 4 || k == 6) && !(last && k >= 4)) { __syncthreads();
;                     CtxResid CE{first ? a.in[2] : XC, XC, XB, ssq_out, gate_l + 1024, bias, gn_l + 1024, dry};
;     ...
;                     if (g.K == 1024) ctx_gemm<1, 4, CtxResid>(lds, g.A + (size_t)T_LAT * 1024, g.Bt, 1024, 32, CE);
;                     else ctx_gemm<1, 11, CtxResid>(lds, g.A + (size_t)T_LAT * FF, g.Bt, FF, 32, CE);
.LBB0_592:
	s_andn2_b64 vcc, exec, s[20:21]
	s_cbranch_vccnz .LBB0_631
	s_cmp_gt_u32 s87, 3
	v_readlane_b32 s4, v246, 38
	s_cselect_b64 s[0:1], -1, 0
	v_readlane_b32 s5, v246, 39
	s_and_b64 s[0:1], s[4:5], s[0:1]
	s_and_b64 vcc, exec, s[0:1]
	s_cbranch_vccnz .LBB0_631
	s_add_u32 s20, s74, 0x400000
	v_readlane_b32 s0, v246, 42
	s_addc_u32 s21, s75, 0
	v_readlane_b32 s1, v246, 43
	s_andn2_b64 vcc, exec, s[0:1]
	s_mov_b64 s[24:25], s[20:21]
	s_waitcnt lgkmcnt(0)
	s_barrier
	s_cbranch_vccnz .LBB0_596
	v_readlane_b32 s0, v246, 34
	v_readlane_b32 s1, v246, 35
	s_load_dwordx2 s[24:25], s[0:1], 0x10

; #define LAS __attribute__((address_space(3)))
;     const int tid = opaque_tid(), w = __builtin_amdgcn_readfirstlane(tid >> 6), lane = tid & 63, r = lane & 31, hh = lane >> 5;
;     constexpr int KW = NCH * 32, BATCH = (NB == 1) ? NCH : 6;
;     LAS float* red = (LAS float*)lds;
;     for (int u = blockIdx.x; u < 8 * ncb; u += gridDim.x) {
;         const int rt = u & 7, cb = cb0 + (u >> 3);
;         const bf16_t* ap = A + (size_t)(32 * rt + r) * K + w * KW + 16 * hh;
;         const bf16_t* bp[NB];
; #pragma unroll
;         for (int nb = 0; nb < NB; ++nb) bp[nb] = Bt + (size_t)E.brow(32 * cb + r, nb) * K + w * KW + 16 * hh;
;         typename Epi::Pre pre[2];
; #pragma unroll
;         for (int jj = 0; jj < 2; ++jj) { const int reg = (tid >> 6) + 8 * jj; pre[jj] = E.prefetch(32 * rt + (reg & 3) + 8 * (reg >> 2) + 4 * hh, 32 * cb + r); }
; __global__ void __launch_bounds__(512, 2) fwd_megakernel(Args a_) {
;     ...
;                 } else if (k == 2) { __syncthreads();
;                     const float* cssq = SSQ + (size_t)(3 * layer + 1) * NR; const float* ccb = CB + (size_t)((layer * 3 + 1) * 2 + 1) * 5632;
;     ...
;                     if (last) { CtxKv2 CE{QKV, cssq, ccb}; ctx_gemm<2, 4, CtxKv2>(lds, XB + (size_t)T_LAT * 1024, g.Bt, 1024, 32, CE); }
;                     else { CtxQkv3 CE{QKV, cssq, ccb, 0.125f * LOG2E}; ctx_gemm<3, 4, CtxQkv3>(lds, XB + (size_t)T_LAT * 1024, g.Bt, 1024, 32, CE); }
.LBB0_632:
	s_and_b64 vcc, exec, s[24:25]
	s_cbranch_vccz .LBB0_642
	s_mul_i32 s0, s86, 3
	s_add_i32 s4, s0, 1
	s_mul_i32 s0, s4, 0x10400
	v_readlane_b32 s5, v247, 10
	s_mul_hi_i32 s1, s4, 0x10400
	s_add_u32 s0, s5, s0
	v_readlane_b32 s5, v247, 11
	s_addc_u32 s1, s5, s1
	s_lshl_b32 s4, s4, 1
	s_or_b32 s4, s4, 1
	s_mul_hi_i32 s5, s4, 0x5800
	s_mulk_i32 s4, 0x5800
	v_readlane_b32 s6, v247, 12
	s_add_u32 s20, s6, s4
	v_readlane_b32 s4, v247, 13
	s_waitcnt lgkmcnt(0)
	s_barrier
	s_addc_u32 s21, s4, s5
	s_getreg_b32 s4, hwreg(HW_REG_HW_ID, 0, 6)
	s_and_b32 s4, s4, 63
	s_lshl_b32 s4, s4, 2
	s_add_i32 s4, s4, 0
	s_add_i32 s4, s4, 0x21040
	v_mov_b32_e32 v1, s4
	ds_read_b32 v1, v1
	v_readlane_b32 s4, v246, 40
	v_readlane_b32 s5, v246, 41
	s_mov_b64 s[24:25], -1
	s_and_b64 vcc, exec, s[4:5]
	s_mov_b32 s15, 0x200000
	s_mov_b64 s[28:29], 0x200000
	s_cbranch_vccz .LBB0_638
	s_mov_b32 s4, -1
	s_waitcnt lgkmcnt(0)
	v_readfirstlane_b32 s5, v1
	v_mbcnt_lo_u32_b32 v2, s4, 0
	v_mbcnt_hi_u32_b32 v2, s4, v2
	v_lshl_add_u32 v3, s5, 6, v2
	s_andn2_b64 vcc, exec, s[98:99]
	v_ashrrev_i32_e32 v2, 6, v3
	s_mov_b32 s14, 0x10000
	v_readfirstlane_b32 s4, v2
	s_cbranch_vccnz .LBB0_637
	s_lshl_b32 s6, s4, 7
	s_ashr_i32 s7, s6, 31
	s_lshl_b64 s[6:7], s[6:7], 1
	s_add_u32 s8, s74, s6
	s_addc_u32 s9, s75, s7
	v_and_b32_e32 v4, 32, v3
	v_mov_b32_e32 v5, v0
	s_add_u32 s6, s46, s6
	v_and_b32_e32 v8, 63, v3
	v_lshl_add_u64 v[6:7], s[8:9], 0, v[4:5]
	s_mov_b64 s[8:9], 0xca00000
	s_addc_u32 s7, s47, s7
	v_and_b32_e32 v70, 31, v3
	v_lshl_add_u64 v[54:55], v[6:7], 0, s[8:9]
	v_lshl_add_u64 v[56:57], s[6:7], 0, v[4:5]
	v_bfe_u32 v4, v3, 6, 2
	v_lshlrev_b32_e32 v5, 1, v2
	v_lshrrev_b32_e32 v3, 3, v3
	v_lshl_add_u32 v72, v8, 2, 0
	v_add_u32_e32 v6, 8, v2
	v_and_b32_e32 v3, 4, v3
	v_lshl_add_u32 v73, v6, 8, v72
	v_and_b32_e32 v74, -8, v5
	v_lshl_add_u32 v75, v2, 8, v72
	v_lshlrev_b32_e32 v2, 1, v6
	v_or_b32_e32 v71, v3, v4
	s_mulk_i32 s4, 0x3000
	v_add_u32_e32 v76, 0x12000, v75
	v_add_u32_e32 v77, 0x15000, v75
	v_add_u32_e32 v78, 0x10000, v75
	v_add_u32_e32 v79, 0x13000, v75
	v_add_u32_e32 v80, 0x16000, v75
	v_add_u32_e32 v81, 0x11000, v75
	v_add_u32_e32 v82, 0x14000, v75
	v_add_u32_e32 v83, 0x17000, v75
	v_or_b32_e32 v84, v74, v4
	v_add_u32_e32 v85, 0x12000, v73
	v_add_u32_e32 v86, 0x15000, v73
	v_add_u32_e32 v87, 0x10000, v73
	v_add_u32_e32 v88, 0x13000, v73
	v_add_u32_e32 v89, 0x16000, v73
	v_add_u32_e32 v90, 0x11000, v73
	v_add_u32_e32 v91, 0x14000, v73
	v_add_u32_e32 v92, 0x17000, v73
	v_and_or_b32 v93, v2, -8, v4
	v_or_b32_e32 v94, 0x4000, v3
	s_lshl_b32 s5, s88, 2
	s_lshl_b32 s6, s88, 5
	v_readlane_b32 s7, v247, 60
	v_readlane_b32 s8, v247, 59
	s_mov_b32 s9, s2

; #define LAS __attribute__((address_space(3)))
;     const int tid = opaque_tid(), w = __builtin_amdgcn_readfirstlane(tid >> 6), lane = tid & 63, r = lane & 31, hh = lane >> 5;
;     constexpr int KW = NCH * 32, BATCH = (NB == 1) ? NCH : 6;
;     LAS float* red = (LAS float*)lds;
;     for (int u = blockIdx.x; u < 8 * ncb; u += gridDim.x) {
;         const int rt = u & 7, cb = cb0 + (u >> 3);
;         const bf16_t* ap = A + (size_t)(32 * rt + r) * K + w * KW + 16 * hh;
;         const bf16_t* bp[NB];
; #pragma unroll
;         for (int nb = 0; nb < NB; ++nb) bp[nb] = Bt + (size_t)E.brow(32 * cb + r, nb) * K + w * KW + 16 * hh;
;         typename Epi::Pre pre[2];
; #pragma unroll
;         for (int jj = 0; jj < 2; ++jj) { const int reg = (tid >> 6) + 8 * jj; pre[jj] = E.prefetch(32 * rt + (reg & 3) + 8 * (reg >> 2) + 4 * hh, 32 * cb + r); }
; __global__ void __launch_bounds__(512, 2) fwd_megakernel(Args a_) {
;     ...
;                 if (k == 2 && conv) { __syncthreads();
;                     CtxGlu CE{UB, SSQ + (size_t)(3 * layer + 1) * NR, CB + (size_t)((layer * 3 + 1) * 2 + 1) * 5632};
;     ...
;                     ctx_gemm<2, 4, CtxGlu>(lds, XB + (size_t)T_LAT * 1024, g.Bt, 1024, 32, CE);
.LBB0_643:
	s_andn2_b64 vcc, exec, s[24:25]
	s_cbranch_vccnz .LBB0_647
	s_waitcnt lgkmcnt(0)
	s_barrier
	s_getreg_b32 s0, hwreg(HW_REG_HW_ID, 0, 6)
	s_and_b32 s0, s0, 63
	s_lshl_b32 s0, s0, 2
	s_add_i32 s0, s0, 0
	s_add_i32 s0, s0, 0x21040
	v_mov_b32_e32 v1, s0
	ds_read_b32 v1, v1
	s_mov_b32 s0, -1
	s_andn2_b64 vcc, exec, s[98:99]
	s_waitcnt lgkmcnt(0)
	v_readfirstlane_b32 s1, v1
	v_mbcnt_lo_u32_b32 v1, s0, 0
	v_mbcnt_hi_u32_b32 v1, s0, v1
	v_lshl_add_u32 v3, s1, 6, v1
	s_nop 0
	v_ashrrev_i32_e32 v2, 6, v3
	s_nop 0
	v_readfirstlane_b32 s4, v2
	s_cbranch_vccnz .LBB0_647
	s_mul_i32 s86, s86, 3
	s_or_b32 s5, s86, 1
	s_mul_i32 s0, s5, 0x10400
	v_readlane_b32 s6, v247, 10
	s_mul_hi_i32 s1, s5, 0x10400
	s_add_u32 s0, s6, s0
	v_readlane_b32 s6, v247, 11
	s_addc_u32 s1, s6, s1
	s_lshl_b32 s5, s5, 1
	s_or_b32 s5, s5, 1
	s_mul_hi_i32 s6, s5, 0x5800
	s_mulk_i32 s5, 0x5800
	v_readlane_b32 s7, v247, 12
	s_add_u32 s20, s7, s5
	v_readlane_b32 s5, v247, 13
	s_addc_u32 s21, s5, s6
	s_lshl_b32 s6, s4, 7
	s_ashr_i32 s7, s6, 31
	s_lshl_b64 s[6:7], s[6:7], 1
	s_add_u32 s8, s74, s6
	s_addc_u32 s9, s75, s7
	v_and_b32_e32 v4, 32, v3
	v_mov_b32_e32 v5, v0
	s_add_u32 s6, s46, s6
	v_lshl_add_u64 v[6:7], s[8:9], 0, v[4:5]
	s_mov_b64 s[8:9], 0xca00000
	s_addc_u32 s7, s47, s7
	v_and_b32_e32 v1, 31, v3
	v_and_b32_e32 v8, 63, v3
	v_lshl_add_u64 v[34:35], v[6:7], 0, s[8:9]
	v_lshl_add_u64 v[36:37], s[6:7], 0, v[4:5]
	v_bfe_u32 v4, v3, 6, 2
	v_lshlrev_b32_e32 v5, 1, v2
	v_lshrrev_b32_e32 v3, 3, v3
	v_add_u32_e32 v6, 8, v2
	v_and_b32_e32 v3, 4, v3
	v_lshl_add_u32 v41, v8, 2, 0
	v_lshlrev_b32_e32 v7, 8, v6
	v_and_b32_e32 v42, -8, v5
	v_lshlrev_b32_e32 v2, 8, v2
	v_lshlrev_b32_e32 v5, 1, v6
	v_or_b32_e32 v40, v3, v4
	s_lshl_b32 s4, s4, 13
	v_or_b32_e32 v43, v42, v4
	v_and_or_b32 v44, v5, -8, v4
	v_or_b32_e32 v45, 0x4000, v3
	s_lshl_b32 s5, s88, 5
	v_add_u32_e32 v46, v41, v2
	v_add_u32_e32 v47, v41, v7
	v_readlane_b32 s6, v247, 60
	s_mov_b32 s7, s2
	s_mov_b32 s11, 0x10000
